# v083 + inter-layer bf16 stream rows relocated into the same XCD's f32 output rows (out + 16 MiB x): last layer's up->down boundary XCD-local too; 8 XCD-local barriers (t=0,4,5,6,8,12,13,14)
# speedup vs baseline: 1.0170x; 1.0009x over previous
;     __device__ __forceinline__ const float* in(int i) const { return *(const __attribute__((address_space(4))) cfptr_t*)(p + 8 * i); }
;     __device__ __forceinline__ float* out() const { return *(const __attribute__((address_space(4))) fptr_t*)(p + 256); }
;     __device__ __forceinline__ unsigned char* ws() const { return *(const __attribute__((address_space(4))) ucptr_t*)(p + 264); }
; __device__ __forceinline__ void run_phase(const KA& A, const Ctx& F, int ph) {
;     ...
;     const int l = (ph - 1) / PPL, k = (ph == 0) ? 20 : (ph - 1) % PPL;
;     unsigned char* wl = F.ws + WS_W + (size_t)l * W_LAYER;
;     const float* hin = (l == 0) ? A.in(0) : F.out;
;     float* hmid = (float*)(F.ws + WS_RMC);
;     int ngemm = 0;
.LBB0_12:
	s_cmp_lt_u32 s70, 9
	s_cbranch_scc1 .Lhin_done
	v_readlane_b32 s0, v254, 0
	v_readlane_b32 s1, v254, 1
	s_and_b32 s2, s86, 7
	s_lshl_b32 s2, s2, 23
	s_add_u32 s0, s0, s2
	s_addc_u32 s1, s1, 0
	s_nop 0
	v_writelane_b32 v254, s0, 0
	v_writelane_b32 v254, s1, 1

;     __device__ __forceinline__ const float* in(int i) const { return *(const __attribute__((address_space(4))) cfptr_t*)(p + 8 * i); }
; __device__ __forceinline__ void run_phase(const KA& A, const Ctx& F, int ph) {
;     ...
;         else { g = pg8::Gemm{PS, (const bf16*)(wl + WO_DN), D, FFH, FFH, FFH}; E.kind = 2; E.base = hmid;
;                E.gi = ((2 * l + 1) << 2) | 1 | ((l == DEPTH - 1) ? 2 : 0); E.gain = (l == DEPTH - 1) ? A.in(31) : A.in(1) + (l + 1) * D; }
.LBB0_240:
	s_or_b32 s18, s6, s11
	v_readlane_b32 s8, v253, 60
	v_readlane_b32 s9, v253, 61
	s_mov_b64 s[6:7], s[8:9]
	s_cmp_lt_u32 s70, 9
	s_cbranch_scc0 .Lstr_fin
	s_and_b32 s0, s80, 7
	s_lshl_b32 s0, s0, 23
	s_add_u32 s6, s6, s0
	s_addc_u32 s7, s7, 0
.Lstr_fin:
	v_readlane_b32 s8, v254, 2
	v_readlane_b32 s9, v254, 3
	s_movk_i32 s20, 0xb00
	v_writelane_b32 v254, s8, 0
	s_mov_b32 s19, 4
	s_mov_b32 s65, 0
	s_mov_b64 s[12:13], 0
	s_mov_b32 s64, 2
	s_mov_b64 s[0:1], -1
	v_writelane_b32 v254, s9, 1
	s_mov_b64 s[8:9], s[82:83]
	s_movk_i32 s16, 0xb00
	v_readlane_b32 s10, v253, 62
	v_readlane_b32 s11, v253, 63

; __global__ void __launch_bounds__(NTHREADS, 2) mega_fwd(Args args) {
;     ...
;         if (ph + 1 < args.ph_hi) {
;     ...
;             for (int e_ = 0; e_ < EXTRA_SYNCS; ++e_) { XcdBarrier b2 = bar; asm volatile("" : "+s"(b2.bar)); int tb_; asm volatile("v_mbcnt_lo_u32_b32 %0, -1, 0\n\tv_mbcnt_hi_u32_b32 %0, -1, %0\n\tv_or_b32 %0, %1, %0" : "=&v"(tb_) : "s"(wv0 << 6)); xcd_barrier(b2, tb_); }
;     ...
;             if (args.ph_lo < 0) { __threadfence(); cg::this_grid().sync(); }
;             { XcdBarrier b2 = bar; asm volatile("" : "+s"(b2.bar)); int tb_; asm volatile("v_mbcnt_lo_u32_b32 %0, -1, 0\n\tv_mbcnt_hi_u32_b32 %0, -1, %0\n\tv_or_b32 %0, %1, %0" : "=&v"(tb_) : "s"(wv0 << 6)); xcd_barrier(b2, tb_); } }
.LBB0_552:
	s_andn2_saveexec_b64 s[4:5], s[4:5]
	s_cbranch_execz .LBB0_8
	s_add_i32 s4, s70, -2
	s_cmp_lt_u32 s4, 15
	s_cbranch_scc0 .Lxb_global
	s_lshr_b32 s5, 0x7171, s4
	s_and_b32 s5, s5, 1
	s_cbranch_scc0 .Lxb_global
	v_readfirstlane_b32 s5, v18
	s_cmp_eq_u32 s5, 0
	s_cbranch_scc0 .Lxb_global
	s_mov_b64 s[0:1], exec
	s_branch .LBB0_7
